# single-active tile paths skip 16 dead v_mov_b64 pass-through copies; plus DPP quad shuffles in cmp pass B (on v26)
# speedup vs baseline: 1.0059x; 1.0054x over previous
; #define LAS __attribute__((address_space(3)))
; template <bool a0, bool a1> __device__ __forceinline__ void af_qk(const LAS unsigned char* kbuf, const unsigned (&kl)[4], const half8 (&qf)[2][4], f32x4 (&s)[2][4]) {
;     const LAS unsigned char* ka[4];
;     { int _ln; asm volatile("v_mov_b32 %0, %1" : "=v"(_ln) : "v"(kl[0]));
;       const int fr_ = _ln & 15, e_ = (_ln >> 4) ^ fr_;
; #pragma unroll
;       for (int ks = 0; ks < 4; ++ks) ka[ks] = kbuf + fr_ * 256 + ((e_ ^ (4 * ks)) << 4); }
;     half8 kf[2][4];
; #pragma unroll
;     for (int ks = 0; ks < 4; ++ks) kf[0][ks] = *(const LAS half8*)(ka[ks]);
; #pragma unroll
;     for (int kt = 0; kt < 4; ++kt) {
;         if (kt < 3) {
; #pragma unroll
;             for (int ks = 0; ks < 4; ++ks) kf[(kt + 1) & 1][ks] = *(const LAS half8*)(ka[ks] + (kt + 1) * 4096); }
;         s[0][kt] = (f32x4){0.f, 0.f, 0.f, 0.f}; s[1][kt] = (f32x4){0.f, 0.f, 0.f, 0.f};
; #pragma unroll
;         for (int ks = 0; ks < 4; ++ks) {
;             if (a0) s[0][kt] = __builtin_amdgcn_mfma_f32_16x16x32_f16(kf[kt & 1][ks], qf[0][ks], s[0][kt], 0, 0, 0);
;             if (a1) s[1][kt] = __builtin_amdgcn_mfma_f32_16x16x32_f16(kf[kt & 1][ks], qf[1][ks], s[1][kt], 0, 0, 0); }
;         __builtin_amdgcn_sched_barrier(0);
;     }
; }
; __device__ __forceinline__ void af_maskraw(f32x4 (&s)[4], int mbase, int mstep, int fq, int hi, int lo) {
; #pragma unroll
;     for (int kt = 0; kt < 4; ++kt)
; #pragma unroll
;         for (int jj = 0; jj < 4; ++jj) { const int met = mbase + mstep * (16 * kt + 4 * fq + jj); s[kt][jj] = (met <= hi && met > lo) ? s[kt][jj] : -3.0e38f; }
; }
.LBB0_594:
	s_cmp_eq_u32 s17, s3
	s_cselect_b64 s[6:7], -1, 0
	s_cmp_le_i32 s16, s97
	s_cselect_b64 s[60:61], -1, 0
	s_and_b64 s[60:61], s[12:13], s[60:61]
	s_or_b64 s[60:61], s[6:7], s[60:61]
	s_and_b32 s6, s23, 0x18000
	s_add_i32 s64, s6, 0
	s_and_b64 s[6:7], s[62:63], s[8:9]
	s_andn2_b64 vcc, exec, s[6:7]
	s_mov_b64 s[6:7], -1
	s_cbranch_vccz .LBB0_610
	s_xor_b64 s[62:63], s[62:63], -1
	s_and_b64 vcc, exec, s[62:63]
	s_cbranch_vccz .Lsk_604
	s_and_b64 vcc, exec, s[8:9]
	s_cbranch_vccnz .Lsk_597
	v_mov_b64_e32 v[132:133], v[48:49]
	v_mov_b64_e32 v[128:129], v[52:53]
	v_mov_b64_e32 v[124:125], v[64:65]
	v_mov_b64_e32 v[120:121], v[68:69]
	v_mov_b64_e32 v[116:117], v[76:77]
	v_mov_b64_e32 v[112:113], v[84:85]
	v_mov_b64_e32 v[108:109], v[88:89]
	v_mov_b64_e32 v[104:105], v[96:97]
	s_andn2_b64 vcc, exec, s[8:9]
	v_mov_b32_e32 v224, v4
	v_mov_b32_e32 v222, v5
	v_mov_b64_e32 v[130:131], v[46:47]
	v_mov_b64_e32 v[126:127], v[50:51]
	v_mov_b64_e32 v[122:123], v[62:63]
	v_mov_b64_e32 v[118:119], v[66:67]
	v_mov_b64_e32 v[114:115], v[74:75]
	v_mov_b64_e32 v[110:111], v[82:83]
	v_mov_b64_e32 v[106:107], v[86:87]
	v_mov_b64_e32 v[102:103], v[94:95]
	s_cbranch_vccnz .LBB0_602
.Lsk_597:
	v_mov_b32 v118, v172
	s_nop 0
	v_and_b32_e32 v119, 15, v118
	v_lshl_add_u32 v122, v119, 8, s64
	v_lshlrev_b32_e32 v119, 4, v119
	v_bitop3_b32 v123, v119, v118, -16 bitop3:0x78
	v_add_u32_e32 v118, v122, v123
	v_xad_u32 v119, v123, 64, v122
	v_xad_u32 v120, v123, s77, v122
	v_xad_u32 v121, v123, s78, v122
	ds_read_b128 v[134:137], v118
	ds_read_b128 v[138:141], v119
	ds_read_b128 v[142:145], v120
	ds_read_b128 v[146:149], v121
	ds_read_b128 v[150:153], v118 offset:4096
	ds_read_b128 v[154:157], v119 offset:4096
	ds_read_b128 v[158:161], v120 offset:4096
	ds_read_b128 v[162:165], v121 offset:4096
	s_waitcnt lgkmcnt(4)
	v_mfma_f32_16x16x32_f16 v[114:117], v[134:137], v[22:25], 0
	v_mfma_f32_16x16x32_f16 v[114:117], v[138:141], v[26:29], v[114:117]
	v_mfma_f32_16x16x32_f16 v[114:117], v[142:145], v[30:33], v[114:117]
	v_mfma_f32_16x16x32_f16 v[114:117], v[146:149], v[34:37], v[114:117]
	ds_read_b128 v[134:137], v118 offset:8192
	ds_read_b128 v[138:141], v119 offset:8192
	ds_read_b128 v[142:145], v120 offset:8192
	ds_read_b128 v[146:149], v121 offset:8192
	s_waitcnt lgkmcnt(4)
	v_mfma_f32_16x16x32_f16 v[110:113], v[150:153], v[22:25], 0
	v_mfma_f32_16x16x32_f16 v[110:113], v[154:157], v[26:29], v[110:113]
	v_mfma_f32_16x16x32_f16 v[110:113], v[158:161], v[30:33], v[110:113]
	v_mfma_f32_16x16x32_f16 v[110:113], v[162:165], v[34:37], v[110:113]
	ds_read_b128 v[150:153], v118 offset:12288
	ds_read_b128 v[154:157], v119 offset:12288
	ds_read_b128 v[158:161], v120 offset:12288
	ds_read_b128 v[162:165], v121 offset:12288
	s_waitcnt lgkmcnt(4)
	v_mfma_f32_16x16x32_f16 v[106:109], v[134:137], v[22:25], 0
	v_mfma_f32_16x16x32_f16 v[106:109], v[138:141], v[26:29], v[106:109]
	v_mfma_f32_16x16x32_f16 v[106:109], v[142:145], v[30:33], v[106:109]
	v_mfma_f32_16x16x32_f16 v[106:109], v[146:149], v[34:37], v[106:109]
	s_waitcnt lgkmcnt(0)
	v_mfma_f32_16x16x32_f16 v[102:105], v[150:153], v[22:25], 0
	v_mfma_f32_16x16x32_f16 v[102:105], v[154:157], v[26:29], v[102:105]
	v_mfma_f32_16x16x32_f16 v[102:105], v[158:161], v[30:33], v[102:105]
	v_mfma_f32_16x16x32_f16 v[102:105], v[162:165], v[34:37], v[102:105]
	s_andn2_b64 vcc, exec, s[60:61]
	s_cbranch_vccnz .LBB0_599
	v_add_u32_e32 v118, s16, v173
	v_cmp_le_i32_e32 vcc, v118, v2
	v_cmp_gt_i32_e64 s[6:7], v118, v218
	s_and_b64 vcc, vcc, s[6:7]
	v_cndmask_b32_e32 v114, v202, v114, vcc
	v_cmp_lt_i32_e32 vcc, v118, v2
	v_cmp_ge_i32_e64 s[6:7], v118, v218
	s_and_b64 vcc, vcc, s[6:7]
	v_add_u32_e32 v119, 2, v118
	v_cndmask_b32_e32 v115, v202, v115, vcc
	v_cmp_le_i32_e32 vcc, v119, v2
	v_cmp_gt_i32_e64 s[6:7], v119, v218
	s_and_b64 vcc, vcc, s[6:7]
	v_add_u32_e32 v119, 3, v118
	v_cndmask_b32_e32 v116, v202, v116, vcc
	v_cmp_le_i32_e32 vcc, v119, v2
	v_cmp_gt_i32_e64 s[6:7], v119, v218
	s_and_b64 vcc, vcc, s[6:7]
	v_add_u32_e32 v119, 16, v118
	v_cndmask_b32_e32 v117, v202, v117, vcc
	v_cmp_le_i32_e32 vcc, v119, v2
	v_cmp_gt_i32_e64 s[6:7], v119, v218
	s_and_b64 vcc, vcc, s[6:7]
	v_add_u32_e32 v119, 17, v118
	v_cndmask_b32_e32 v110, v202, v110, vcc
	v_cmp_le_i32_e32 vcc, v119, v2
	v_cmp_gt_i32_e64 s[6:7], v119, v218
	s_and_b64 vcc, vcc, s[6:7]
	v_add_u32_e32 v119, 18, v118
	v_cndmask_b32_e32 v111, v202, v111, vcc
	v_cmp_le_i32_e32 vcc, v119, v2
	v_cmp_gt_i32_e64 s[6:7], v119, v218
	s_and_b64 vcc, vcc, s[6:7]
	v_add_u32_e32 v119, 19, v118
	v_cndmask_b32_e32 v112, v202, v112, vcc
	v_cmp_le_i32_e32 vcc, v119, v2
	v_cmp_gt_i32_e64 s[6:7], v119, v218
	s_and_b64 vcc, vcc, s[6:7]
	v_add_u32_e32 v119, 32, v118
	v_cndmask_b32_e32 v113, v202, v113, vcc
	v_cmp_le_i32_e32 vcc, v119, v2
	v_cmp_gt_i32_e64 s[6:7], v119, v218
	s_and_b64 vcc, vcc, s[6:7]
	v_add_u32_e32 v119, 33, v118
	v_cndmask_b32_e32 v106, v202, v106, vcc
	v_cmp_le_i32_e32 vcc, v119, v2
	v_cmp_gt_i32_e64 s[6:7], v119, v218
	s_and_b64 vcc, vcc, s[6:7]
	v_add_u32_e32 v119, 34, v118
	v_cndmask_b32_e32 v107, v202, v107, vcc
	v_cmp_le_i32_e32 vcc, v119, v2
	v_cmp_gt_i32_e64 s[6:7], v119, v218
	s_and_b64 vcc, vcc, s[6:7]
	v_add_u32_e32 v119, 35, v118
	v_cndmask_b32_e32 v108, v202, v108, vcc
	v_cmp_le_i32_e32 vcc, v119, v2
	v_cmp_gt_i32_e64 s[6:7], v119, v218
	s_and_b64 vcc, vcc, s[6:7]
	v_add_u32_e32 v119, 48, v118
	v_cndmask_b32_e32 v109, v202, v109, vcc
	v_cmp_le_i32_e32 vcc, v119, v2
	v_cmp_gt_i32_e64 s[6:7], v119, v218
	s_and_b64 vcc, vcc, s[6:7]
	v_add_u32_e32 v119, 49, v118
	v_cndmask_b32_e32 v102, v202, v102, vcc
	v_cmp_le_i32_e32 vcc, v119, v2
	v_cmp_gt_i32_e64 s[6:7], v119, v218
	s_and_b64 vcc, vcc, s[6:7]
	v_add_u32_e32 v119, 50, v118
	v_cndmask_b32_e32 v103, v202, v103, vcc
	v_cmp_le_i32_e32 vcc, v119, v2
	v_cmp_gt_i32_e64 s[6:7], v119, v218
	s_and_b64 vcc, vcc, s[6:7]
	v_add_u32_e32 v118, 51, v118
	v_cndmask_b32_e32 v104, v202, v104, vcc
	v_cmp_le_i32_e32 vcc, v118, v2
	v_cmp_gt_i32_e64 s[6:7], v118, v218
	s_and_b64 vcc, vcc, s[6:7]
	v_cndmask_b32_e32 v105, v202, v105, vcc

; #define LAS __attribute__((address_space(3)))
; template <bool a0, bool a1> __device__ __forceinline__ void af_qk(const LAS unsigned char* kbuf, const unsigned (&kl)[4], const half8 (&qf)[2][4], f32x4 (&s)[2][4]) {
;     const LAS unsigned char* ka[4];
;     { int _ln; asm volatile("v_mov_b32 %0, %1" : "=v"(_ln) : "v"(kl[0]));
;       const int fr_ = _ln & 15, e_ = (_ln >> 4) ^ fr_;
; #pragma unroll
;       for (int ks = 0; ks < 4; ++ks) ka[ks] = kbuf + fr_ * 256 + ((e_ ^ (4 * ks)) << 4); }
;     half8 kf[2][4];
; #pragma unroll
;     for (int ks = 0; ks < 4; ++ks) kf[0][ks] = *(const LAS half8*)(ka[ks]);
; #pragma unroll
;     for (int kt = 0; kt < 4; ++kt) {
;         if (kt < 3) {
; #pragma unroll
;             for (int ks = 0; ks < 4; ++ks) kf[(kt + 1) & 1][ks] = *(const LAS half8*)(ka[ks] + (kt + 1) * 4096); }
;         s[0][kt] = (f32x4){0.f, 0.f, 0.f, 0.f}; s[1][kt] = (f32x4){0.f, 0.f, 0.f, 0.f};
; #pragma unroll
;         for (int ks = 0; ks < 4; ++ks) {
;             if (a0) s[0][kt] = __builtin_amdgcn_mfma_f32_16x16x32_f16(kf[kt & 1][ks], qf[0][ks], s[0][kt], 0, 0, 0);
;             if (a1) s[1][kt] = __builtin_amdgcn_mfma_f32_16x16x32_f16(kf[kt & 1][ks], qf[1][ks], s[1][kt], 0, 0, 0); }
;         __builtin_amdgcn_sched_barrier(0);
;     }
; }
; __device__ __forceinline__ void af_maskraw(f32x4 (&s)[4], int mbase, int mstep, int fq, int hi, int lo) {
; #pragma unroll
;     for (int kt = 0; kt < 4; ++kt)
; #pragma unroll
;         for (int jj = 0; jj < 4; ++jj) { const int met = mbase + mstep * (16 * kt + 4 * fq + jj); s[kt][jj] = (met <= hi && met > lo) ? s[kt][jj] : -3.0e38f; }
; }
.Lsk_604:
	v_mov_b32 v114, v172
	s_nop 0
	v_and_b32_e32 v115, 15, v114
	v_lshl_add_u32 v118, v115, 8, s64
	v_lshlrev_b32_e32 v115, 4, v115
	v_bitop3_b32 v119, v115, v114, -16 bitop3:0x78
	v_add_u32_e32 v114, v118, v119
	v_xad_u32 v115, v119, 64, v118
	v_xad_u32 v116, v119, s77, v118
	v_xad_u32 v117, v119, s78, v118
	ds_read_b128 v[134:137], v114
	ds_read_b128 v[138:141], v115
	ds_read_b128 v[142:145], v116
	ds_read_b128 v[146:149], v117
	ds_read_b128 v[150:153], v114 offset:4096
	ds_read_b128 v[154:157], v115 offset:4096
	ds_read_b128 v[158:161], v116 offset:4096
	ds_read_b128 v[162:165], v117 offset:4096
	s_waitcnt lgkmcnt(4)
	v_mfma_f32_16x16x32_f16 v[122:125], v[134:137], v[6:9], 0
	v_mfma_f32_16x16x32_f16 v[122:125], v[138:141], v[10:13], v[122:125]
	v_mfma_f32_16x16x32_f16 v[122:125], v[142:145], v[14:17], v[122:125]
	v_mfma_f32_16x16x32_f16 v[122:125], v[146:149], v[18:21], v[122:125]
	ds_read_b128 v[134:137], v114 offset:8192
	ds_read_b128 v[138:141], v115 offset:8192
	ds_read_b128 v[142:145], v116 offset:8192
	ds_read_b128 v[146:149], v117 offset:8192
	s_waitcnt lgkmcnt(4)
	v_mfma_f32_16x16x32_f16 v[110:113], v[150:153], v[6:9], 0
	v_mfma_f32_16x16x32_f16 v[110:113], v[154:157], v[10:13], v[110:113]
	v_mfma_f32_16x16x32_f16 v[110:113], v[158:161], v[14:17], v[110:113]
	v_mfma_f32_16x16x32_f16 v[110:113], v[162:165], v[18:21], v[110:113]
	ds_read_b128 v[150:153], v114 offset:12288
	ds_read_b128 v[154:157], v115 offset:12288
	ds_read_b128 v[158:161], v116 offset:12288
	ds_read_b128 v[162:165], v117 offset:12288
	s_waitcnt lgkmcnt(4)
	v_mfma_f32_16x16x32_f16 v[106:109], v[134:137], v[6:9], 0
	v_mfma_f32_16x16x32_f16 v[106:109], v[138:141], v[10:13], v[106:109]
	v_mfma_f32_16x16x32_f16 v[106:109], v[142:145], v[14:17], v[106:109]
	v_mfma_f32_16x16x32_f16 v[106:109], v[146:149], v[18:21], v[106:109]
	s_waitcnt lgkmcnt(0)
	v_mfma_f32_16x16x32_f16 v[102:105], v[150:153], v[6:9], 0
	v_mfma_f32_16x16x32_f16 v[102:105], v[154:157], v[10:13], v[102:105]
	v_mfma_f32_16x16x32_f16 v[102:105], v[158:161], v[14:17], v[102:105]
	v_mfma_f32_16x16x32_f16 v[102:105], v[162:165], v[18:21], v[102:105]
	s_andn2_b64 vcc, exec, s[60:61]
	s_cbranch_vccnz .LBB0_606
	v_add_u32_e32 v114, s16, v173
	v_cmp_le_i32_e32 vcc, v114, v219
	v_cmp_gt_i32_e64 s[6:7], v114, v220
	s_and_b64 vcc, vcc, s[6:7]
	v_cndmask_b32_e32 v122, v202, v122, vcc
	v_cmp_lt_i32_e32 vcc, v114, v219
	v_cmp_ge_i32_e64 s[6:7], v114, v220
	s_and_b64 vcc, vcc, s[6:7]
	v_add_u32_e32 v115, 2, v114
	v_cndmask_b32_e32 v123, v202, v123, vcc
	v_cmp_le_i32_e32 vcc, v115, v219
	v_cmp_gt_i32_e64 s[6:7], v115, v220
	s_and_b64 vcc, vcc, s[6:7]
	v_add_u32_e32 v115, 3, v114
	v_cndmask_b32_e32 v124, v202, v124, vcc
	v_cmp_le_i32_e32 vcc, v115, v219
	v_cmp_gt_i32_e64 s[6:7], v115, v220
	s_and_b64 vcc, vcc, s[6:7]
	v_add_u32_e32 v115, 16, v114
	v_cndmask_b32_e32 v125, v202, v125, vcc
	v_cmp_le_i32_e32 vcc, v115, v219
	v_cmp_gt_i32_e64 s[6:7], v115, v220
	s_and_b64 vcc, vcc, s[6:7]
	v_add_u32_e32 v115, 17, v114
	v_cndmask_b32_e32 v110, v202, v110, vcc
	v_cmp_le_i32_e32 vcc, v115, v219
	v_cmp_gt_i32_e64 s[6:7], v115, v220
	s_and_b64 vcc, vcc, s[6:7]
	v_add_u32_e32 v115, 18, v114
	v_cndmask_b32_e32 v111, v202, v111, vcc
	v_cmp_le_i32_e32 vcc, v115, v219
	v_cmp_gt_i32_e64 s[6:7], v115, v220
	s_and_b64 vcc, vcc, s[6:7]
	v_add_u32_e32 v115, 19, v114
	v_cndmask_b32_e32 v112, v202, v112, vcc
	v_cmp_le_i32_e32 vcc, v115, v219
	v_cmp_gt_i32_e64 s[6:7], v115, v220
	s_and_b64 vcc, vcc, s[6:7]
	v_add_u32_e32 v115, 32, v114
	v_cndmask_b32_e32 v113, v202, v113, vcc
	v_cmp_le_i32_e32 vcc, v115, v219
	v_cmp_gt_i32_e64 s[6:7], v115, v220
	s_and_b64 vcc, vcc, s[6:7]
	v_add_u32_e32 v115, 33, v114
	v_cndmask_b32_e32 v106, v202, v106, vcc
	v_cmp_le_i32_e32 vcc, v115, v219
	v_cmp_gt_i32_e64 s[6:7], v115, v220
	s_and_b64 vcc, vcc, s[6:7]
	v_add_u32_e32 v115, 34, v114
	v_cndmask_b32_e32 v107, v202, v107, vcc
	v_cmp_le_i32_e32 vcc, v115, v219
	v_cmp_gt_i32_e64 s[6:7], v115, v220
	s_and_b64 vcc, vcc, s[6:7]
	v_add_u32_e32 v115, 35, v114
	v_cndmask_b32_e32 v108, v202, v108, vcc
	v_cmp_le_i32_e32 vcc, v115, v219
	v_cmp_gt_i32_e64 s[6:7], v115, v220
	s_and_b64 vcc, vcc, s[6:7]
	v_add_u32_e32 v115, 48, v114
	v_cndmask_b32_e32 v109, v202, v109, vcc
	v_cmp_le_i32_e32 vcc, v115, v219
	v_cmp_gt_i32_e64 s[6:7], v115, v220
	s_and_b64 vcc, vcc, s[6:7]
	v_add_u32_e32 v115, 49, v114
	v_cndmask_b32_e32 v102, v202, v102, vcc
	v_cmp_le_i32_e32 vcc, v115, v219
	v_cmp_gt_i32_e64 s[6:7], v115, v220
	s_and_b64 vcc, vcc, s[6:7]
	v_add_u32_e32 v115, 50, v114
	v_cndmask_b32_e32 v103, v202, v103, vcc
	v_cmp_le_i32_e32 vcc, v115, v219
	v_cmp_gt_i32_e64 s[6:7], v115, v220
	s_and_b64 vcc, vcc, s[6:7]
	v_add_u32_e32 v114, 51, v114
	v_cndmask_b32_e32 v104, v202, v104, vcc
	v_cmp_le_i32_e32 vcc, v114, v219
	v_cmp_gt_i32_e64 s[6:7], v114, v220
	s_and_b64 vcc, vcc, s[6:7]
	v_cndmask_b32_e32 v105, v202, v105, vcc

; #define LAS __attribute__((address_space(3)))
; template <bool a0, bool a1> __device__ __forceinline__ void af_qk(const LAS unsigned char* kbuf, const unsigned (&kl)[4], const half8 (&qf)[2][4], f32x4 (&s)[2][4]) {
;     const LAS unsigned char* ka[4];
;     { int _ln; asm volatile("v_mov_b32 %0, %1" : "=v"(_ln) : "v"(kl[0]));
;       const int fr_ = _ln & 15, e_ = (_ln >> 4) ^ fr_;
; #pragma unroll
;       for (int ks = 0; ks < 4; ++ks) ka[ks] = kbuf + fr_ * 256 + ((e_ ^ (4 * ks)) << 4); }
;     half8 kf[2][4];
; #pragma unroll
;     for (int ks = 0; ks < 4; ++ks) kf[0][ks] = *(const LAS half8*)(ka[ks]);
; #pragma unroll
;     for (int kt = 0; kt < 4; ++kt) {
;         if (kt < 3) {
; #pragma unroll
;             for (int ks = 0; ks < 4; ++ks) kf[(kt + 1) & 1][ks] = *(const LAS half8*)(ka[ks] + (kt + 1) * 4096); }
;         s[0][kt] = (f32x4){0.f, 0.f, 0.f, 0.f}; s[1][kt] = (f32x4){0.f, 0.f, 0.f, 0.f};
; #pragma unroll
;         for (int ks = 0; ks < 4; ++ks) {
;             if (a0) s[0][kt] = __builtin_amdgcn_mfma_f32_16x16x32_f16(kf[kt & 1][ks], qf[0][ks], s[0][kt], 0, 0, 0);
;             if (a1) s[1][kt] = __builtin_amdgcn_mfma_f32_16x16x32_f16(kf[kt & 1][ks], qf[1][ks], s[1][kt], 0, 0, 0); }
;         __builtin_amdgcn_sched_barrier(0);
;     }
; }
; __device__ __forceinline__ void af_maskraw(f32x4 (&s)[4], int mbase, int mstep, int fq, int hi, int lo) {
; #pragma unroll
;     for (int kt = 0; kt < 4; ++kt)
; #pragma unroll
;         for (int jj = 0; jj < 4; ++jj) { const int met = mbase + mstep * (16 * kt + 4 * fq + jj); s[kt][jj] = (met <= hi && met > lo) ? s[kt][jj] : -3.0e38f; }
; }
.Lu2_594:
	s_cmp_eq_u32 s17, s3
	s_cselect_b64 s[6:7], -1, 0
	s_cmp_le_i32 s16, s97
	s_cselect_b64 s[60:61], -1, 0
	s_and_b64 s[60:61], s[12:13], s[60:61]
	s_or_b64 s[60:61], s[6:7], s[60:61]
	s_and_b32 s6, s23, 0x18000
	s_add_i32 s64, s6, 0
	s_and_b64 s[6:7], s[62:63], s[8:9]
	s_andn2_b64 vcc, exec, s[6:7]
	s_mov_b64 s[6:7], -1
	s_cbranch_vccz .Lu2_610
	s_xor_b64 s[62:63], s[62:63], -1
	s_and_b64 vcc, exec, s[62:63]
	s_cbranch_vccz .Lu2_604
	s_and_b64 vcc, exec, s[8:9]
	s_cbranch_vccnz .Lu2_597
	v_mov_b64_e32 v[48:49], v[132:133]
	v_mov_b64_e32 v[52:53], v[128:129]
	v_mov_b64_e32 v[64:65], v[124:125]
	v_mov_b64_e32 v[68:69], v[120:121]
	v_mov_b64_e32 v[76:77], v[116:117]
	v_mov_b64_e32 v[84:85], v[112:113]
	v_mov_b64_e32 v[88:89], v[108:109]
	v_mov_b64_e32 v[96:97], v[104:105]
	s_andn2_b64 vcc, exec, s[8:9]
	v_mov_b32_e32 v224, v4
	v_mov_b32_e32 v222, v5
	v_mov_b64_e32 v[46:47], v[130:131]
	v_mov_b64_e32 v[50:51], v[126:127]
	v_mov_b64_e32 v[62:63], v[122:123]
	v_mov_b64_e32 v[66:67], v[118:119]
	v_mov_b64_e32 v[74:75], v[114:115]
	v_mov_b64_e32 v[82:83], v[110:111]
	v_mov_b64_e32 v[86:87], v[106:107]
	v_mov_b64_e32 v[94:95], v[102:103]
	s_cbranch_vccnz .Lu2_602
.Lu2_597:
	v_mov_b32 v66, v172
	s_nop 0
	v_and_b32_e32 v67, 15, v66
	v_lshl_add_u32 v62, v67, 8, s64
	v_lshlrev_b32_e32 v67, 4, v67
	v_bitop3_b32 v63, v67, v66, -16 bitop3:0x78
	v_add_u32_e32 v66, v62, v63
	v_xad_u32 v67, v63, 64, v62
	v_xad_u32 v68, v63, s77, v62
	v_xad_u32 v69, v63, s78, v62
	ds_read_b128 v[98:101], v66
	ds_read_b128 v[90:93], v67
	ds_read_b128 v[78:81], v68
	ds_read_b128 v[70:73], v69
	ds_read_b128 v[58:61], v66 offset:4096
	ds_read_b128 v[54:57], v67 offset:4096
	ds_read_b128 v[42:45], v68 offset:4096
	ds_read_b128 v[38:41], v69 offset:4096
	s_waitcnt lgkmcnt(4)
	v_mfma_f32_16x16x32_f16 v[74:77], v[98:101], v[22:25], 0
	v_mfma_f32_16x16x32_f16 v[74:77], v[90:93], v[26:29], v[74:77]
	v_mfma_f32_16x16x32_f16 v[74:77], v[78:81], v[30:33], v[74:77]
	v_mfma_f32_16x16x32_f16 v[74:77], v[70:73], v[34:37], v[74:77]
	ds_read_b128 v[98:101], v66 offset:8192
	ds_read_b128 v[90:93], v67 offset:8192
	ds_read_b128 v[78:81], v68 offset:8192
	ds_read_b128 v[70:73], v69 offset:8192
	s_waitcnt lgkmcnt(4)
	v_mfma_f32_16x16x32_f16 v[82:85], v[58:61], v[22:25], 0
	v_mfma_f32_16x16x32_f16 v[82:85], v[54:57], v[26:29], v[82:85]
	v_mfma_f32_16x16x32_f16 v[82:85], v[42:45], v[30:33], v[82:85]
	v_mfma_f32_16x16x32_f16 v[82:85], v[38:41], v[34:37], v[82:85]
	ds_read_b128 v[58:61], v66 offset:12288
	ds_read_b128 v[54:57], v67 offset:12288
	ds_read_b128 v[42:45], v68 offset:12288
	ds_read_b128 v[38:41], v69 offset:12288
	s_waitcnt lgkmcnt(4)
	v_mfma_f32_16x16x32_f16 v[86:89], v[98:101], v[22:25], 0
	v_mfma_f32_16x16x32_f16 v[86:89], v[90:93], v[26:29], v[86:89]
	v_mfma_f32_16x16x32_f16 v[86:89], v[78:81], v[30:33], v[86:89]
	v_mfma_f32_16x16x32_f16 v[86:89], v[70:73], v[34:37], v[86:89]
	s_waitcnt lgkmcnt(0)
	v_mfma_f32_16x16x32_f16 v[94:97], v[58:61], v[22:25], 0
	v_mfma_f32_16x16x32_f16 v[94:97], v[54:57], v[26:29], v[94:97]
	v_mfma_f32_16x16x32_f16 v[94:97], v[42:45], v[30:33], v[94:97]
	v_mfma_f32_16x16x32_f16 v[94:97], v[38:41], v[34:37], v[94:97]
	s_andn2_b64 vcc, exec, s[60:61]
	s_cbranch_vccnz .Lu2_599
	v_add_u32_e32 v66, s16, v173
	v_cmp_le_i32_e32 vcc, v66, v2
	v_cmp_gt_i32_e64 s[6:7], v66, v218
	s_and_b64 vcc, vcc, s[6:7]
	v_cndmask_b32_e32 v74, v202, v74, vcc
	v_cmp_lt_i32_e32 vcc, v66, v2
	v_cmp_ge_i32_e64 s[6:7], v66, v218
	s_and_b64 vcc, vcc, s[6:7]
	v_add_u32_e32 v67, 2, v66
	v_cndmask_b32_e32 v75, v202, v75, vcc
	v_cmp_le_i32_e32 vcc, v67, v2
	v_cmp_gt_i32_e64 s[6:7], v67, v218
	s_and_b64 vcc, vcc, s[6:7]
	v_add_u32_e32 v67, 3, v66
	v_cndmask_b32_e32 v76, v202, v76, vcc
	v_cmp_le_i32_e32 vcc, v67, v2
	v_cmp_gt_i32_e64 s[6:7], v67, v218
	s_and_b64 vcc, vcc, s[6:7]
	v_add_u32_e32 v67, 16, v66
	v_cndmask_b32_e32 v77, v202, v77, vcc
	v_cmp_le_i32_e32 vcc, v67, v2
	v_cmp_gt_i32_e64 s[6:7], v67, v218
	s_and_b64 vcc, vcc, s[6:7]
	v_add_u32_e32 v67, 17, v66
	v_cndmask_b32_e32 v82, v202, v82, vcc
	v_cmp_le_i32_e32 vcc, v67, v2
	v_cmp_gt_i32_e64 s[6:7], v67, v218
	s_and_b64 vcc, vcc, s[6:7]
	v_add_u32_e32 v67, 18, v66
	v_cndmask_b32_e32 v83, v202, v83, vcc
	v_cmp_le_i32_e32 vcc, v67, v2
	v_cmp_gt_i32_e64 s[6:7], v67, v218
	s_and_b64 vcc, vcc, s[6:7]
	v_add_u32_e32 v67, 19, v66
	v_cndmask_b32_e32 v84, v202, v84, vcc
	v_cmp_le_i32_e32 vcc, v67, v2
	v_cmp_gt_i32_e64 s[6:7], v67, v218
	s_and_b64 vcc, vcc, s[6:7]
	v_add_u32_e32 v67, 32, v66
	v_cndmask_b32_e32 v85, v202, v85, vcc
	v_cmp_le_i32_e32 vcc, v67, v2
	v_cmp_gt_i32_e64 s[6:7], v67, v218
	s_and_b64 vcc, vcc, s[6:7]
	v_add_u32_e32 v67, 33, v66
	v_cndmask_b32_e32 v86, v202, v86, vcc
	v_cmp_le_i32_e32 vcc, v67, v2
	v_cmp_gt_i32_e64 s[6:7], v67, v218
	s_and_b64 vcc, vcc, s[6:7]
	v_add_u32_e32 v67, 34, v66
	v_cndmask_b32_e32 v87, v202, v87, vcc
	v_cmp_le_i32_e32 vcc, v67, v2
	v_cmp_gt_i32_e64 s[6:7], v67, v218
	s_and_b64 vcc, vcc, s[6:7]
	v_add_u32_e32 v67, 35, v66
	v_cndmask_b32_e32 v88, v202, v88, vcc
	v_cmp_le_i32_e32 vcc, v67, v2
	v_cmp_gt_i32_e64 s[6:7], v67, v218
	s_and_b64 vcc, vcc, s[6:7]
	v_add_u32_e32 v67, 48, v66
	v_cndmask_b32_e32 v89, v202, v89, vcc
	v_cmp_le_i32_e32 vcc, v67, v2
	v_cmp_gt_i32_e64 s[6:7], v67, v218
	s_and_b64 vcc, vcc, s[6:7]
	v_add_u32_e32 v67, 49, v66
	v_cndmask_b32_e32 v94, v202, v94, vcc
	v_cmp_le_i32_e32 vcc, v67, v2
	v_cmp_gt_i32_e64 s[6:7], v67, v218
	s_and_b64 vcc, vcc, s[6:7]
	v_add_u32_e32 v67, 50, v66
	v_cndmask_b32_e32 v95, v202, v95, vcc
	v_cmp_le_i32_e32 vcc, v67, v2
	v_cmp_gt_i32_e64 s[6:7], v67, v218
	s_and_b64 vcc, vcc, s[6:7]
	v_add_u32_e32 v66, 51, v66
	v_cndmask_b32_e32 v96, v202, v96, vcc
	v_cmp_le_i32_e32 vcc, v66, v2
	v_cmp_gt_i32_e64 s[6:7], v66, v218
	s_and_b64 vcc, vcc, s[6:7]
	v_cndmask_b32_e32 v97, v202, v97, vcc

; #define LAS __attribute__((address_space(3)))
; template <bool a0, bool a1> __device__ __forceinline__ void af_qk(const LAS unsigned char* kbuf, const unsigned (&kl)[4], const half8 (&qf)[2][4], f32x4 (&s)[2][4]) {
;     const LAS unsigned char* ka[4];
;     { int _ln; asm volatile("v_mov_b32 %0, %1" : "=v"(_ln) : "v"(kl[0]));
;       const int fr_ = _ln & 15, e_ = (_ln >> 4) ^ fr_;
; #pragma unroll
;       for (int ks = 0; ks < 4; ++ks) ka[ks] = kbuf + fr_ * 256 + ((e_ ^ (4 * ks)) << 4); }
;     half8 kf[2][4];
; #pragma unroll
;     for (int ks = 0; ks < 4; ++ks) kf[0][ks] = *(const LAS half8*)(ka[ks]);
; #pragma unroll
;     for (int kt = 0; kt < 4; ++kt) {
;         if (kt < 3) {
; #pragma unroll
;             for (int ks = 0; ks < 4; ++ks) kf[(kt + 1) & 1][ks] = *(const LAS half8*)(ka[ks] + (kt + 1) * 4096); }
;         s[0][kt] = (f32x4){0.f, 0.f, 0.f, 0.f}; s[1][kt] = (f32x4){0.f, 0.f, 0.f, 0.f};
; #pragma unroll
;         for (int ks = 0; ks < 4; ++ks) {
;             if (a0) s[0][kt] = __builtin_amdgcn_mfma_f32_16x16x32_f16(kf[kt & 1][ks], qf[0][ks], s[0][kt], 0, 0, 0);
;             if (a1) s[1][kt] = __builtin_amdgcn_mfma_f32_16x16x32_f16(kf[kt & 1][ks], qf[1][ks], s[1][kt], 0, 0, 0); }
;         __builtin_amdgcn_sched_barrier(0);
;     }
; }
; __device__ __forceinline__ void af_maskraw(f32x4 (&s)[4], int mbase, int mstep, int fq, int hi, int lo) {
; #pragma unroll
;     for (int kt = 0; kt < 4; ++kt)
; #pragma unroll
;         for (int jj = 0; jj < 4; ++jj) { const int met = mbase + mstep * (16 * kt + 4 * fq + jj); s[kt][jj] = (met <= hi && met > lo) ? s[kt][jj] : -3.0e38f; }
; }
.Lu2_604:
	v_mov_b32 v74, v172
	s_nop 0
	v_and_b32_e32 v75, 15, v74
	v_lshl_add_u32 v66, v75, 8, s64
	v_lshlrev_b32_e32 v75, 4, v75
	v_bitop3_b32 v67, v75, v74, -16 bitop3:0x78
	v_add_u32_e32 v74, v66, v67
	v_xad_u32 v75, v67, 64, v66
	v_xad_u32 v76, v67, s77, v66
	v_xad_u32 v77, v67, s78, v66
	ds_read_b128 v[98:101], v74
	ds_read_b128 v[90:93], v75
	ds_read_b128 v[78:81], v76
	ds_read_b128 v[70:73], v77
	ds_read_b128 v[58:61], v74 offset:4096
	ds_read_b128 v[54:57], v75 offset:4096
	ds_read_b128 v[42:45], v76 offset:4096
	ds_read_b128 v[38:41], v77 offset:4096
	s_waitcnt lgkmcnt(4)
	v_mfma_f32_16x16x32_f16 v[62:65], v[98:101], v[6:9], 0
	v_mfma_f32_16x16x32_f16 v[62:65], v[90:93], v[10:13], v[62:65]
	v_mfma_f32_16x16x32_f16 v[62:65], v[78:81], v[14:17], v[62:65]
	v_mfma_f32_16x16x32_f16 v[62:65], v[70:73], v[18:21], v[62:65]
	ds_read_b128 v[98:101], v74 offset:8192
	ds_read_b128 v[90:93], v75 offset:8192
	ds_read_b128 v[78:81], v76 offset:8192
	ds_read_b128 v[70:73], v77 offset:8192
	s_waitcnt lgkmcnt(4)
	v_mfma_f32_16x16x32_f16 v[82:85], v[58:61], v[6:9], 0
	v_mfma_f32_16x16x32_f16 v[82:85], v[54:57], v[10:13], v[82:85]
	v_mfma_f32_16x16x32_f16 v[82:85], v[42:45], v[14:17], v[82:85]
	v_mfma_f32_16x16x32_f16 v[82:85], v[38:41], v[18:21], v[82:85]
	ds_read_b128 v[58:61], v74 offset:12288
	ds_read_b128 v[54:57], v75 offset:12288
	ds_read_b128 v[42:45], v76 offset:12288
	ds_read_b128 v[38:41], v77 offset:12288
	s_waitcnt lgkmcnt(4)
	v_mfma_f32_16x16x32_f16 v[86:89], v[98:101], v[6:9], 0
	v_mfma_f32_16x16x32_f16 v[86:89], v[90:93], v[10:13], v[86:89]
	v_mfma_f32_16x16x32_f16 v[86:89], v[78:81], v[14:17], v[86:89]
	v_mfma_f32_16x16x32_f16 v[86:89], v[70:73], v[18:21], v[86:89]
	s_waitcnt lgkmcnt(0)
	v_mfma_f32_16x16x32_f16 v[94:97], v[58:61], v[6:9], 0
	v_mfma_f32_16x16x32_f16 v[94:97], v[54:57], v[10:13], v[94:97]
	v_mfma_f32_16x16x32_f16 v[94:97], v[42:45], v[14:17], v[94:97]
	v_mfma_f32_16x16x32_f16 v[94:97], v[38:41], v[18:21], v[94:97]
	s_andn2_b64 vcc, exec, s[60:61]
	s_cbranch_vccnz .Lu2_606
	v_add_u32_e32 v74, s16, v173
	v_cmp_le_i32_e32 vcc, v74, v219
	v_cmp_gt_i32_e64 s[6:7], v74, v220
	s_and_b64 vcc, vcc, s[6:7]
	v_cndmask_b32_e32 v62, v202, v62, vcc
	v_cmp_lt_i32_e32 vcc, v74, v219
	v_cmp_ge_i32_e64 s[6:7], v74, v220
	s_and_b64 vcc, vcc, s[6:7]
	v_add_u32_e32 v75, 2, v74
	v_cndmask_b32_e32 v63, v202, v63, vcc
	v_cmp_le_i32_e32 vcc, v75, v219
	v_cmp_gt_i32_e64 s[6:7], v75, v220
	s_and_b64 vcc, vcc, s[6:7]
	v_add_u32_e32 v75, 3, v74
	v_cndmask_b32_e32 v64, v202, v64, vcc
	v_cmp_le_i32_e32 vcc, v75, v219
	v_cmp_gt_i32_e64 s[6:7], v75, v220
	s_and_b64 vcc, vcc, s[6:7]
	v_add_u32_e32 v75, 16, v74
	v_cndmask_b32_e32 v65, v202, v65, vcc
	v_cmp_le_i32_e32 vcc, v75, v219
	v_cmp_gt_i32_e64 s[6:7], v75, v220
	s_and_b64 vcc, vcc, s[6:7]
	v_add_u32_e32 v75, 17, v74
	v_cndmask_b32_e32 v82, v202, v82, vcc
	v_cmp_le_i32_e32 vcc, v75, v219
	v_cmp_gt_i32_e64 s[6:7], v75, v220
	s_and_b64 vcc, vcc, s[6:7]
	v_add_u32_e32 v75, 18, v74
	v_cndmask_b32_e32 v83, v202, v83, vcc
	v_cmp_le_i32_e32 vcc, v75, v219
	v_cmp_gt_i32_e64 s[6:7], v75, v220
	s_and_b64 vcc, vcc, s[6:7]
	v_add_u32_e32 v75, 19, v74
	v_cndmask_b32_e32 v84, v202, v84, vcc
	v_cmp_le_i32_e32 vcc, v75, v219
	v_cmp_gt_i32_e64 s[6:7], v75, v220
	s_and_b64 vcc, vcc, s[6:7]
	v_add_u32_e32 v75, 32, v74
	v_cndmask_b32_e32 v85, v202, v85, vcc
	v_cmp_le_i32_e32 vcc, v75, v219
	v_cmp_gt_i32_e64 s[6:7], v75, v220
	s_and_b64 vcc, vcc, s[6:7]
	v_add_u32_e32 v75, 33, v74
	v_cndmask_b32_e32 v86, v202, v86, vcc
	v_cmp_le_i32_e32 vcc, v75, v219
	v_cmp_gt_i32_e64 s[6:7], v75, v220
	s_and_b64 vcc, vcc, s[6:7]
	v_add_u32_e32 v75, 34, v74
	v_cndmask_b32_e32 v87, v202, v87, vcc
	v_cmp_le_i32_e32 vcc, v75, v219
	v_cmp_gt_i32_e64 s[6:7], v75, v220
	s_and_b64 vcc, vcc, s[6:7]
	v_add_u32_e32 v75, 35, v74
	v_cndmask_b32_e32 v88, v202, v88, vcc
	v_cmp_le_i32_e32 vcc, v75, v219
	v_cmp_gt_i32_e64 s[6:7], v75, v220
	s_and_b64 vcc, vcc, s[6:7]
	v_add_u32_e32 v75, 48, v74
	v_cndmask_b32_e32 v89, v202, v89, vcc
	v_cmp_le_i32_e32 vcc, v75, v219
	v_cmp_gt_i32_e64 s[6:7], v75, v220
	s_and_b64 vcc, vcc, s[6:7]
	v_add_u32_e32 v75, 49, v74
	v_cndmask_b32_e32 v94, v202, v94, vcc
	v_cmp_le_i32_e32 vcc, v75, v219
	v_cmp_gt_i32_e64 s[6:7], v75, v220
	s_and_b64 vcc, vcc, s[6:7]
	v_add_u32_e32 v75, 50, v74
	v_cndmask_b32_e32 v95, v202, v95, vcc
	v_cmp_le_i32_e32 vcc, v75, v219
	v_cmp_gt_i32_e64 s[6:7], v75, v220
	s_and_b64 vcc, vcc, s[6:7]
	v_add_u32_e32 v74, 51, v74
	v_cndmask_b32_e32 v96, v202, v96, vcc
	v_cmp_le_i32_e32 vcc, v74, v219
	v_cmp_gt_i32_e64 s[6:7], v74, v220
	s_and_b64 vcc, vcc, s[6:7]
	v_cndmask_b32_e32 v97, v202, v97, vcc
